# K-loop heads of the four GEMM bodies aligned to 64 bytes (p2align 6 before the loop labels)
# speedup vs baseline: 1.0217x; 1.0036x over previous
.Lprio_skip_out:
	.p2align	6
